# M2 normalisation: the four cross-row ds_bpermute hops replaced by v_permlane16/32 swaps (bit-identical)
# speedup vs baseline: 1.0013x; 1.0013x over previous
.LBB0_555:
	s_and_b32 s0, s4, 7
	s_lshl_b32 s1, s0, 2
	v_readlane_b32 s4, v255, 37
	v_mov_b32_e32 v60, s1
	v_readlane_b32 s5, v255, 38
	v_ashrrev_i32_e32 v155, 31, v154
	s_nop 3
	s_lshl_b32 s18, s0, 8
	s_load_dword s22, s[4:5], s1
	s_load_dword s0, s[4:5], s1 offset:0x20
	v_readlane_b32 s4, v252, 22
	v_ashrrev_i32_e32 v177, 4, v2
	v_lshlrev_b64 v[0:1], 11, v[154:155]
	v_readlane_b32 s5, v252, 23
	v_lshlrev_b32_e32 v172, 2, v177
	v_lshl_add_u64 v[0:1], s[4:5], 0, v[0:1]
	v_lshl_add_u64 v[0:1], v[0:1], 0, s[18:19]
	v_ashrrev_i32_e32 v173, 31, v172
	v_lshl_add_u64 v[0:1], v[172:173], 1, v[0:1]
	global_load_dwordx2 v[162:163], v[0:1], off
	global_load_dwordx2 v[160:161], v[0:1], off offset:32
	global_load_dwordx2 v[158:159], v[0:1], off offset:64
	global_load_dwordx2 v[156:157], v[0:1], off offset:96
	global_load_dwordx2 v[152:153], v[0:1], off offset:128
	global_load_dwordx2 v[150:151], v[0:1], off offset:160
	global_load_dwordx2 v[148:149], v[0:1], off offset:192
	s_nop 0
	global_load_dwordx2 v[0:1], v[0:1], off offset:224
	v_mul_u32_u24_e32 v62, 0xa0, v175
	v_and_b32_e32 v155, -16, v2
	v_add_u32_e32 v60, 1, v180
	v_sub_u32_e32 v61, 0x80, v180
	v_add3_u32 v136, 0, v62, v155
	v_cvt_f32_i32_e32 v124, v60
	v_cvt_f32_i32_e32 v125, v61
	s_waitcnt lgkmcnt(0)
	v_mov_b32_e32 v116, s22
	v_mov_b32_e32 v117, s0
	ds_read_b128 v[60:63], v136 offset:26624
	ds_read_b128 v[64:67], v136 offset:26688
	ds_read_b128 v[68:71], v136 offset:47104
	ds_read_b128 v[72:75], v136 offset:47168
	ds_read_b128 v[76:79], v136 offset:29184
	ds_read_b128 v[80:83], v136 offset:29248
	ds_read_b128 v[84:87], v136 offset:49664
	ds_read_b128 v[88:91], v136 offset:49728
	ds_read_b128 v[92:95], v136 offset:31744
	ds_read_b128 v[96:99], v136 offset:31808
	ds_read_b128 v[100:103], v136 offset:52224
	ds_read_b128 v[104:107], v136 offset:52288
	ds_read_b128 v[108:111], v136 offset:34304
	ds_read_b128 v[112:115], v136 offset:34368
	v_mul_f32_e32 v116, 0x3fb8aa3b, v116
	v_mul_f32_e32 v117, 0x3fb8aa3b, v117
	v_exp_f32_e32 v173, v116
	v_exp_f32_e32 v176, v117
	ds_read_b128 v[116:119], v136 offset:54784
	ds_read_b128 v[120:123], v136 offset:54848
	v_mul_f32_e64 v124, v124, -v173
	v_mul_f32_e64 v125, v125, -v176
	v_mul_f32_e32 v124, 0x3fb8aa3b, v124
	v_mul_f32_e32 v125, 0x3fb8aa3b, v125
	v_exp_f32_e32 v140, v124
	v_exp_f32_e32 v142, v125
	s_waitcnt lgkmcnt(14)
	v_mfma_f32_16x16x32_bf16 v[60:63], v[60:63], v[56:59], 0
	v_mfma_f32_16x16x32_bf16 v[60:63], v[64:67], v[52:55], v[60:63]
	s_waitcnt lgkmcnt(13)
	v_mfma_f32_16x16x32_bf16 v[64:67], v[68:71], v[56:59], 0
	s_waitcnt lgkmcnt(12)
	v_mfma_f32_16x16x32_bf16 v[64:67], v[72:75], v[52:55], v[64:67]
	s_waitcnt lgkmcnt(9)
	v_mfma_f32_16x16x32_bf16 v[72:75], v[84:87], v[56:59], 0
	v_mfma_f32_16x16x32_bf16 v[68:71], v[76:79], v[56:59], 0
	s_nop 4
	v_mul_f32_e64 v64, v142, v64
	v_mul_f32_e64 v65, v142, v65
	v_pk_mul_f32 v[66:67], v[142:143], v[66:67] op_sel_hi:[0,1]
	v_pk_fma_f32 v[60:61], v[140:141], v[60:61], v[64:65] op_sel_hi:[0,1,1]
	s_waitcnt lgkmcnt(8)
	v_mfma_f32_16x16x32_bf16 v[72:75], v[88:91], v[52:55], v[72:75]
	v_fma_f32 v62, v140, v62, v66
	v_fma_f32 v63, v140, v63, v67
	v_mfma_f32_16x16x32_bf16 v[68:71], v[80:83], v[52:55], v[68:71]
	s_waitcnt lgkmcnt(5)
	v_mfma_f32_16x16x32_bf16 v[80:83], v[100:103], v[56:59], 0
	s_nop 2
	v_mul_f32_e64 v64, v142, v74
	v_mul_f32_e64 v65, v142, v75
	v_pk_mul_f32 v[72:73], v[142:143], v[72:73] op_sel_hi:[0,1]
	v_pk_fma_f32 v[66:67], v[140:141], v[70:71], v[64:65] op_sel_hi:[0,1,1]
	v_mfma_f32_16x16x32_bf16 v[76:79], v[92:95], v[56:59], 0
	v_fma_f32 v64, v140, v68, v72
	v_fma_f32 v65, v140, v69, v73
	s_waitcnt lgkmcnt(1)
	v_mfma_f32_16x16x32_bf16 v[72:75], v[116:119], v[56:59], 0
	v_mfma_f32_16x16x32_bf16 v[80:83], v[104:107], v[52:55], v[80:83]
	v_mfma_f32_16x16x32_bf16 v[76:79], v[96:99], v[52:55], v[76:79]
	v_mfma_f32_16x16x32_bf16 v[84:87], v[108:111], v[56:59], 0
	s_nop 5
	v_mul_f32_e64 v68, v142, v82
	v_mul_f32_e64 v69, v142, v83
	v_pk_mul_f32 v[80:81], v[142:143], v[80:81] op_sel_hi:[0,1]
	v_pk_fma_f32 v[70:71], v[140:141], v[78:79], v[68:69] op_sel_hi:[0,1,1]
	s_waitcnt lgkmcnt(0)
	v_mfma_f32_16x16x32_bf16 v[72:75], v[120:123], v[52:55], v[72:75]
	v_fma_f32 v68, v140, v76, v80
	v_fma_f32 v69, v140, v77, v81
	s_nop 5
	v_pk_mul_f32 v[76:77], v[142:143], v[74:75] op_sel_hi:[0,1]
	v_pk_mul_f32 v[78:79], v[142:143], v[72:73] op_sel_hi:[0,1]
	v_mfma_f32_16x16x32_bf16 v[72:75], v[112:115], v[52:55], v[84:87]
	s_nop 7
	v_pk_fma_f32 v[74:75], v[140:141], v[74:75], v[76:77] op_sel_hi:[0,1,1]
	v_pk_fma_f32 v[72:73], v[140:141], v[72:73], v[78:79] op_sel_hi:[0,1,1]
	ds_read_b128 v[76:79], v136 offset:36864
	ds_read_b128 v[80:83], v136 offset:36928
	ds_read_b128 v[84:87], v136 offset:57344
	ds_read_b128 v[88:91], v136 offset:57408
	ds_read_b128 v[92:95], v136 offset:39424
	ds_read_b128 v[96:99], v136 offset:39488
	ds_read_b128 v[100:103], v136 offset:59904
	ds_read_b128 v[104:107], v136 offset:59968
	ds_read_b128 v[108:111], v136 offset:41984
	ds_read_b128 v[112:115], v136 offset:42048
	ds_read_b128 v[116:119], v136 offset:62464
	ds_read_b128 v[120:123], v136 offset:62528
	ds_read_b128 v[124:127], v136 offset:44544
	ds_read_b128 v[128:131], v136 offset:44608
	ds_read_b128 v[132:135], v136 offset:65024
	ds_read_b128 v[136:139], v136 offset:65088
	s_waitcnt lgkmcnt(14)
	v_mfma_f32_16x16x32_bf16 v[76:79], v[76:79], v[56:59], 0
	v_mfma_f32_16x16x32_bf16 v[76:79], v[80:83], v[52:55], v[76:79]
	s_waitcnt lgkmcnt(13)
	v_mfma_f32_16x16x32_bf16 v[80:83], v[84:87], v[56:59], 0
	s_waitcnt lgkmcnt(12)
	v_mfma_f32_16x16x32_bf16 v[80:83], v[88:91], v[52:55], v[80:83]
	s_waitcnt lgkmcnt(9)
	v_mfma_f32_16x16x32_bf16 v[88:91], v[100:103], v[56:59], 0
	v_mfma_f32_16x16x32_bf16 v[84:87], v[92:95], v[56:59], 0
	s_nop 4
	v_mul_f32_e64 v80, v142, v80
	v_mul_f32_e64 v81, v142, v81
	v_pk_mul_f32 v[82:83], v[142:143], v[82:83] op_sel_hi:[0,1]
	v_pk_fma_f32 v[76:77], v[140:141], v[76:77], v[80:81] op_sel_hi:[0,1,1]
	s_waitcnt lgkmcnt(8)
	v_mfma_f32_16x16x32_bf16 v[88:91], v[104:107], v[52:55], v[88:91]
	v_fma_f32 v78, v140, v78, v82
	v_fma_f32 v79, v140, v79, v83
	v_mfma_f32_16x16x32_bf16 v[84:87], v[96:99], v[52:55], v[84:87]
	s_waitcnt lgkmcnt(5)
	v_mfma_f32_16x16x32_bf16 v[96:99], v[116:119], v[56:59], 0
	s_nop 2
	v_mul_f32_e64 v80, v142, v90
	v_mul_f32_e64 v81, v142, v91
	v_pk_mul_f32 v[88:89], v[142:143], v[88:89] op_sel_hi:[0,1]
	v_pk_fma_f32 v[82:83], v[140:141], v[86:87], v[80:81] op_sel_hi:[0,1,1]
	v_mfma_f32_16x16x32_bf16 v[92:95], v[108:111], v[56:59], 0
	v_fma_f32 v80, v140, v84, v88
	v_fma_f32 v81, v140, v85, v89
	s_waitcnt lgkmcnt(1)
	v_mfma_f32_16x16x32_bf16 v[88:91], v[132:135], v[56:59], 0
	v_mfma_f32_16x16x32_bf16 v[96:99], v[120:123], v[52:55], v[96:99]
	v_mfma_f32_16x16x32_bf16 v[92:95], v[112:115], v[52:55], v[92:95]
	v_mfma_f32_16x16x32_bf16 v[100:103], v[124:127], v[56:59], 0
	s_nop 5
	v_mul_f32_e64 v84, v142, v98
	v_mul_f32_e64 v85, v142, v99
	v_pk_mul_f32 v[96:97], v[142:143], v[96:97] op_sel_hi:[0,1]
	v_pk_fma_f32 v[86:87], v[140:141], v[94:95], v[84:85] op_sel_hi:[0,1,1]
	s_waitcnt lgkmcnt(0)
	v_mfma_f32_16x16x32_bf16 v[88:91], v[136:139], v[52:55], v[88:91]
	v_fma_f32 v84, v140, v92, v96
	v_fma_f32 v85, v140, v93, v97
	s_nop 5
	v_pk_mul_f32 v[92:93], v[142:143], v[90:91] op_sel_hi:[0,1]
	v_pk_mul_f32 v[94:95], v[142:143], v[88:89] op_sel_hi:[0,1]
	v_mfma_f32_16x16x32_bf16 v[88:91], v[128:131], v[52:55], v[100:103]
	s_nop 7
	v_pk_fma_f32 v[90:91], v[140:141], v[90:91], v[92:93] op_sel_hi:[0,1,1]
	v_pk_fma_f32 v[88:89], v[140:141], v[88:89], v[94:95] op_sel_hi:[0,1,1]
	v_lshlrev_b32_e32 v93, 1, v2
	v_lshlrev_b32_e32 v92, 1, v175
	v_and_b32_e32 v93, 6, v93
	v_and_or_b32 v92, v92, 24, v93
	v_mul_u32_u24_e32 v92, 0xd0, v92
	v_add3_u32 v96, 0, v92, v155
	ds_read_b128 v[92:95], v96
	ds_read_b128 v[144:147], v96 offset:64
	ds_read_b128 v[182:185], v96 offset:208
	ds_read_b128 v[186:189], v96 offset:272
	ds_read_b128 v[140:143], v96 offset:6656
	ds_read_b128 v[136:139], v96 offset:6720
	ds_read_b128 v[132:135], v96 offset:6864
	ds_read_b128 v[112:115], v96 offset:6928
	ds_read_b128 v[128:131], v96 offset:13312
	ds_read_b128 v[124:127], v96 offset:13376
	ds_read_b128 v[120:123], v96 offset:13520
	ds_read_b128 v[116:119], v96 offset:13584
	ds_read_b128 v[108:111], v96 offset:19968
	ds_read_b128 v[104:107], v96 offset:20032
	ds_read_b128 v[100:103], v96 offset:20176
	ds_read_b128 v[96:99], v96 offset:20240
	v_lshlrev_b32_e32 v178, 3, v177
	v_sub_u32_e32 v179, v180, v178
	v_sub_u32_e32 v169, 0, v179
	v_max_i32_e32 v169, v179, v169
	v_cvt_f32_u32_e32 v169, v169
	v_cmp_gt_i32_e32 vcc, 0, v179
	v_add_u32_e32 v168, -1, v179
	s_waitcnt lgkmcnt(14)
	v_mfma_f32_16x16x32_bf16 v[92:95], v[92:95], v[56:59], 0
	v_cndmask_b32_e32 v181, v173, v176, vcc
	v_mul_f32_e64 v169, -v181, v169
	v_cmp_lt_i32_e32 vcc, 0, v179
	v_sub_u32_e32 v181, 1, v179
	v_mfma_f32_16x16x32_bf16 v[92:95], v[144:147], v[52:55], v[92:95]
	v_cndmask_b32_e32 v168, v181, v168, vcc
	v_cvt_f32_u32_e32 v168, v168
	v_cndmask_b32_e32 v181, v176, v173, vcc
	s_waitcnt lgkmcnt(13)
	v_mfma_f32_16x16x32_bf16 v[144:147], v[182:185], v[56:59], 0
	v_mul_f32_e32 v169, 0x3fb8aa3b, v169
	v_mul_f32_e64 v168, -v181, v168
	v_mul_f32_e32 v168, 0x3fb8aa3b, v168
	v_exp_f32_e32 v168, v168
	s_waitcnt lgkmcnt(12)
	v_mfma_f32_16x16x32_bf16 v[144:147], v[186:189], v[52:55], v[144:147]
	v_exp_f32_e32 v169, v169
	v_or_b32_e32 v181, 1, v178
	s_movk_i32 s22, 0x70
	v_cmp_gt_i32_e64 s[0:1], s22, v181
	v_cmp_gt_i32_e32 vcc, 14, v177
	s_and_b64 s[0:1], s[2:3], s[0:1]
	s_and_b64 s[4:5], s[2:3], vcc
	v_cndmask_b32_e64 v168, v168, 0, s[0:1]
	v_cndmask_b32_e64 v169, v169, 0, s[4:5]
	v_mul_f32_e32 v144, v168, v144
	v_or_b32_e32 v168, 2, v178
	v_mul_f32_e32 v92, v169, v92
	v_sub_u32_e32 v169, v180, v168
	v_sub_u32_e32 v182, 0, v169
	v_cmp_gt_i32_e32 vcc, 0, v169
	v_add_u32_e32 v181, -1, v169
	v_max_i32_e32 v182, v169, v182
	v_cndmask_b32_e32 v183, v173, v176, vcc
	v_cmp_lt_i32_e32 vcc, 0, v169
	v_sub_u32_e32 v169, 1, v169
	v_cvt_f32_u32_e32 v182, v182
	v_cndmask_b32_e32 v169, v169, v181, vcc
	v_cvt_f32_u32_e32 v169, v169
	v_cndmask_b32_e32 v181, v176, v173, vcc
	v_mul_f32_e64 v182, -v183, v182
	v_mul_f32_e32 v182, 0x3fb8aa3b, v182
	v_mul_f32_e64 v169, -v181, v169
	v_exp_f32_e32 v182, v182
	v_mul_f32_e32 v169, 0x3fb8aa3b, v169
	v_exp_f32_e32 v169, v169
	v_cmp_gt_i32_e32 vcc, s22, v168
	v_or_b32_e32 v168, 3, v178
	v_cmp_gt_i32_e64 s[0:1], s22, v168
	s_and_b64 s[4:5], s[2:3], vcc
	v_cndmask_b32_e64 v168, v182, 0, s[4:5]
	s_and_b64 s[0:1], s[2:3], s[0:1]
	v_cndmask_b32_e64 v169, v169, 0, s[0:1]
	v_mul_f32_e32 v93, v168, v93
	v_or_b32_e32 v168, 4, v178
	v_mul_f32_e32 v145, v169, v145
	v_sub_u32_e32 v169, v180, v168
	v_sub_u32_e32 v182, 0, v169
	v_cmp_gt_i32_e32 vcc, 0, v169
	v_add_u32_e32 v181, -1, v169
	v_max_i32_e32 v182, v169, v182
	v_cndmask_b32_e32 v183, v173, v176, vcc
	v_cmp_lt_i32_e32 vcc, 0, v169
	v_sub_u32_e32 v169, 1, v169
	v_cvt_f32_u32_e32 v182, v182
	v_cndmask_b32_e32 v169, v169, v181, vcc
	v_cvt_f32_u32_e32 v169, v169
	v_cndmask_b32_e32 v181, v176, v173, vcc
	v_mul_f32_e64 v182, -v183, v182
	v_mul_f32_e32 v182, 0x3fb8aa3b, v182
	v_mul_f32_e64 v169, -v181, v169
	v_exp_f32_e32 v182, v182
	v_mul_f32_e32 v169, 0x3fb8aa3b, v169
	v_exp_f32_e32 v169, v169
	v_cmp_gt_i32_e32 vcc, s22, v168
	v_or_b32_e32 v168, 5, v178
	v_cmp_gt_i32_e64 s[0:1], s22, v168
	s_and_b64 s[4:5], s[2:3], vcc
	v_cndmask_b32_e64 v168, v182, 0, s[4:5]
	s_and_b64 s[0:1], s[2:3], s[0:1]
	v_cndmask_b32_e64 v169, v169, 0, s[0:1]
	v_mul_f32_e32 v94, v168, v94
	v_or_b32_e32 v168, 6, v178
	s_waitcnt lgkmcnt(9)
	v_mfma_f32_16x16x32_bf16 v[132:135], v[132:135], v[56:59], 0
	v_mul_f32_e32 v146, v169, v146
	v_sub_u32_e32 v169, v180, v168
	v_sub_u32_e32 v181, 0, v169
	v_cmp_gt_i32_e32 vcc, 0, v169
	v_add_u32_e32 v180, -1, v169
	v_max_i32_e32 v181, v169, v181
	v_cndmask_b32_e32 v182, v173, v176, vcc
	v_cmp_lt_i32_e32 vcc, 0, v169
	v_sub_u32_e32 v169, 1, v169
	s_waitcnt lgkmcnt(8)
	v_mfma_f32_16x16x32_bf16 v[112:115], v[112:115], v[52:55], v[132:135]
	v_cndmask_b32_e32 v169, v169, v180, vcc
	v_cndmask_b32_e32 v180, v176, v173, vcc
	v_cmp_gt_i32_e32 vcc, s22, v168
	v_subrev_u32_e32 v132, 32, v179
	s_and_b64 s[4:5], s[2:3], vcc
	v_sub_u32_e32 v134, 32, v179
	v_cmp_gt_i32_e32 vcc, 0, v132
	v_cvt_f32_u32_e32 v169, v169
	v_subrev_u32_e32 v133, 33, v179
	v_max_i32_e32 v134, v132, v134
	v_cndmask_b32_e32 v135, v173, v176, vcc
	v_cmp_lt_i32_e32 vcc, 0, v132
	v_sub_u32_e32 v132, 33, v179
	v_cvt_f32_u32_e32 v181, v181
	v_cndmask_b32_e32 v132, v132, v133, vcc
	v_cvt_f32_u32_e32 v132, v132
	v_mul_f32_e64 v169, -v180, v169
	v_cvt_f32_u32_e32 v134, v134
	v_mul_f32_e32 v169, 0x3fb8aa3b, v169
	v_cndmask_b32_e32 v133, v176, v173, vcc
	v_exp_f32_e32 v169, v169
	v_mul_f32_e64 v132, -v133, v132
	v_mul_f32_e64 v181, -v182, v181
	v_or_b32_e32 v168, 7, v178
	v_mfma_f32_16x16x32_bf16 v[140:143], v[140:143], v[56:59], 0
	v_mul_f32_e32 v132, 0x3fb8aa3b, v132
	v_mul_f32_e32 v181, 0x3fb8aa3b, v181
	v_cmp_gt_i32_e64 s[0:1], s22, v168
	v_mul_f32_e64 v134, -v135, v134
	v_exp_f32_e32 v132, v132
	v_exp_f32_e32 v181, v181
	s_and_b64 s[0:1], s[2:3], s[0:1]
	v_mul_f32_e32 v134, 0x3fb8aa3b, v134
	v_add_u32_e32 v133, 33, v178
	v_cndmask_b32_e64 v169, v169, 0, s[0:1]
	v_exp_f32_e32 v134, v134
	v_cmp_gt_i32_e64 s[0:1], s22, v133
	v_mfma_f32_16x16x32_bf16 v[136:139], v[136:139], v[52:55], v[140:143]
	s_and_b64 s[0:1], s[2:3], s[0:1]
	v_cmp_gt_i32_e32 vcc, 10, v177
	v_cndmask_b32_e64 v132, v132, 0, s[0:1]
	v_cndmask_b32_e64 v168, v181, 0, s[4:5]
	s_and_b64 s[4:5], s[2:3], vcc
	v_mul_f32_e32 v112, v132, v112
	v_subrev_u32_e32 v132, 34, v179
	v_cndmask_b32_e64 v133, v134, 0, s[4:5]
	v_sub_u32_e32 v135, 34, v179
	v_cmp_gt_i32_e32 vcc, 0, v132
	v_mul_f32_e32 v133, v133, v136
	v_subrev_u32_e32 v134, 35, v179
	v_max_i32_e32 v135, v132, v135
	v_cndmask_b32_e32 v136, v173, v176, vcc
	v_cmp_lt_i32_e32 vcc, 0, v132
	v_sub_u32_e32 v132, 35, v179
	v_cvt_f32_u32_e32 v135, v135
	v_cndmask_b32_e32 v132, v132, v134, vcc
	v_cvt_f32_u32_e32 v132, v132
	v_cndmask_b32_e32 v134, v176, v173, vcc
	v_mul_f32_e64 v135, -v136, v135
	v_mul_f32_e32 v135, 0x3fb8aa3b, v135
	v_mul_f32_e64 v132, -v134, v132
	v_mul_f32_e32 v132, 0x3fb8aa3b, v132
	v_exp_f32_e32 v132, v132
	v_add_u32_e32 v134, 35, v178
	v_exp_f32_e32 v135, v135
	v_cmp_gt_i32_e32 vcc, s22, v134
	s_and_b64 s[0:1], s[2:3], vcc
	v_cndmask_b32_e64 v132, v132, 0, s[0:1]
	v_mul_f32_e32 v113, v132, v113
	v_subrev_u32_e32 v132, 36, v179
	v_cndmask_b32_e64 v134, v135, 0, s[4:5]
	v_sub_u32_e32 v136, 36, v179
	v_cmp_gt_i32_e32 vcc, 0, v132
	v_mul_f32_e32 v134, v134, v137
	v_subrev_u32_e32 v135, 37, v179
	v_max_i32_e32 v136, v132, v136
	v_cndmask_b32_e32 v137, v173, v176, vcc
	v_cmp_lt_i32_e32 vcc, 0, v132
	v_sub_u32_e32 v132, 37, v179
	v_cvt_f32_u32_e32 v136, v136
	v_cndmask_b32_e32 v132, v132, v135, vcc
	v_cvt_f32_u32_e32 v132, v132
	v_cndmask_b32_e32 v135, v176, v173, vcc
	v_mul_f32_e64 v136, -v137, v136
	v_mul_f32_e32 v136, 0x3fb8aa3b, v136
	v_mul_f32_e64 v132, -v135, v132
	v_mul_f32_e32 v132, 0x3fb8aa3b, v132
	v_exp_f32_e32 v132, v132
	v_add_u32_e32 v135, 37, v178
	v_exp_f32_e32 v136, v136
	v_cmp_gt_i32_e32 vcc, s22, v135
	s_and_b64 s[0:1], s[2:3], vcc
	v_cndmask_b32_e64 v132, v132, 0, s[0:1]
	v_mul_f32_e32 v114, v132, v114
	v_subrev_u32_e32 v132, 38, v179
	v_cndmask_b32_e64 v135, v136, 0, s[4:5]
	v_sub_u32_e32 v137, 38, v179
	v_cmp_gt_i32_e32 vcc, 0, v132
	v_mul_f32_e32 v135, v135, v138
	v_subrev_u32_e32 v136, 39, v179
	v_max_i32_e32 v137, v132, v137
	v_cndmask_b32_e32 v138, v173, v176, vcc
	v_cmp_lt_i32_e32 vcc, 0, v132
	v_sub_u32_e32 v132, 39, v179
	s_waitcnt lgkmcnt(5)
	v_mfma_f32_16x16x32_bf16 v[120:123], v[120:123], v[56:59], 0
	v_cndmask_b32_e32 v132, v132, v136, vcc
	v_cvt_f32_u32_e32 v132, v132
	v_cndmask_b32_e32 v136, v176, v173, vcc
	s_waitcnt lgkmcnt(4)
	v_mfma_f32_16x16x32_bf16 v[116:119], v[116:119], v[52:55], v[120:123]
	v_cvt_f32_u32_e32 v137, v137
	v_mul_f32_e64 v132, -v136, v132
	v_add_u32_e32 v136, 39, v178
	v_cmp_gt_i32_e32 vcc, s22, v136
	v_subrev_u32_e32 v120, 64, v179
	s_and_b64 s[0:1], s[2:3], vcc
	v_sub_u32_e32 v122, 64, v179
	v_cmp_gt_i32_e32 vcc, 0, v120
	v_add_u32_e32 v121, 0xffffffbf, v179
	v_max_i32_e32 v122, v120, v122
	v_cndmask_b32_e32 v123, v173, v176, vcc
	v_cmp_lt_i32_e32 vcc, 0, v120
	v_sub_u32_e32 v120, 0x41, v179
	v_cvt_f32_u32_e32 v122, v122
	v_cndmask_b32_e32 v120, v120, v121, vcc
	v_cvt_f32_u32_e32 v120, v120
	v_mul_f32_e32 v132, 0x3fb8aa3b, v132
	v_cndmask_b32_e32 v121, v176, v173, vcc
	v_exp_f32_e32 v132, v132
	v_mul_f32_e64 v120, -v121, v120
	v_mul_f32_e64 v137, -v138, v137
	v_mfma_f32_16x16x32_bf16 v[128:131], v[128:131], v[56:59], 0
	v_mul_f32_e32 v120, 0x3fb8aa3b, v120
	v_mul_f32_e32 v137, 0x3fb8aa3b, v137
	v_mul_f32_e64 v122, -v123, v122
	v_exp_f32_e32 v120, v120
	v_exp_f32_e32 v137, v137
	v_mul_f32_e32 v122, 0x3fb8aa3b, v122
	v_add_u32_e32 v121, 0x41, v178
	v_cndmask_b32_e64 v132, v132, 0, s[0:1]
	v_exp_f32_e32 v122, v122
	v_cmp_gt_i32_e64 s[0:1], s22, v121
	v_mfma_f32_16x16x32_bf16 v[124:127], v[124:127], v[52:55], v[128:131]
	s_and_b64 s[0:1], s[2:3], s[0:1]
	v_cmp_gt_i32_e32 vcc, 6, v177
	v_cndmask_b32_e64 v120, v120, 0, s[0:1]
	v_cndmask_b32_e64 v136, v137, 0, s[4:5]
	s_and_b64 s[4:5], s[2:3], vcc
	v_mul_f32_e32 v116, v120, v116
	v_add_u32_e32 v120, 0xffffffbe, v179
	v_cndmask_b32_e64 v121, v122, 0, s[4:5]
	v_sub_u32_e32 v123, 0x42, v179
	v_cmp_gt_i32_e32 vcc, 0, v120
	v_mul_f32_e32 v121, v121, v124
	v_add_u32_e32 v122, 0xffffffbd, v179
	v_max_i32_e32 v123, v120, v123
	v_cndmask_b32_e32 v124, v173, v176, vcc
	v_cmp_lt_i32_e32 vcc, 0, v120
	v_sub_u32_e32 v120, 0x43, v179
	v_cvt_f32_u32_e32 v123, v123
	v_cndmask_b32_e32 v120, v120, v122, vcc
	v_cvt_f32_u32_e32 v120, v120
	v_cndmask_b32_e32 v122, v176, v173, vcc
	v_mul_f32_e64 v123, -v124, v123
	v_mul_f32_e32 v123, 0x3fb8aa3b, v123
	v_mul_f32_e64 v120, -v122, v120
	v_mul_f32_e32 v120, 0x3fb8aa3b, v120
	v_exp_f32_e32 v120, v120
	v_add_u32_e32 v122, 0x43, v178
	v_exp_f32_e32 v123, v123
	v_cmp_gt_i32_e32 vcc, s22, v122
	s_and_b64 s[0:1], s[2:3], vcc
	v_cndmask_b32_e64 v120, v120, 0, s[0:1]
	v_mul_f32_e32 v117, v120, v117
	v_add_u32_e32 v120, 0xffffffbc, v179
	v_cndmask_b32_e64 v122, v123, 0, s[4:5]
	v_sub_u32_e32 v124, 0x44, v179
	v_cmp_gt_i32_e32 vcc, 0, v120
	v_mul_f32_e32 v122, v122, v125
	v_add_u32_e32 v123, 0xffffffbb, v179
	v_max_i32_e32 v124, v120, v124
	v_cndmask_b32_e32 v125, v173, v176, vcc
	v_cmp_lt_i32_e32 vcc, 0, v120
	v_sub_u32_e32 v120, 0x45, v179
	v_cvt_f32_u32_e32 v124, v124
	v_cndmask_b32_e32 v120, v120, v123, vcc
	v_cvt_f32_u32_e32 v120, v120
	v_cndmask_b32_e32 v123, v176, v173, vcc
	v_mul_f32_e64 v124, -v125, v124
	v_mul_f32_e32 v124, 0x3fb8aa3b, v124
	v_mul_f32_e64 v120, -v123, v120
	v_mul_f32_e32 v120, 0x3fb8aa3b, v120
	v_exp_f32_e32 v120, v120
	v_add_u32_e32 v123, 0x45, v178
	v_exp_f32_e32 v124, v124
	v_cmp_gt_i32_e32 vcc, s22, v123
	s_and_b64 s[0:1], s[2:3], vcc
	v_cndmask_b32_e64 v120, v120, 0, s[0:1]
	v_mul_f32_e32 v118, v120, v118
	v_add_u32_e32 v120, 0xffffffba, v179
	v_cndmask_b32_e64 v123, v124, 0, s[4:5]
	v_sub_u32_e32 v125, 0x46, v179
	v_cmp_gt_i32_e32 vcc, 0, v120
	v_mul_f32_e32 v123, v123, v126
	v_add_u32_e32 v124, 0xffffffb9, v179
	v_max_i32_e32 v125, v120, v125
	v_cndmask_b32_e32 v126, v173, v176, vcc
	v_cmp_lt_i32_e32 vcc, 0, v120
	v_sub_u32_e32 v120, 0x47, v179
	s_waitcnt lgkmcnt(3)
	v_mfma_f32_16x16x32_bf16 v[108:111], v[108:111], v[56:59], 0
	v_cndmask_b32_e32 v120, v120, v124, vcc
	v_cvt_f32_u32_e32 v120, v120
	v_cndmask_b32_e32 v124, v176, v173, vcc
	s_waitcnt lgkmcnt(1)
	v_mfma_f32_16x16x32_bf16 v[56:59], v[100:103], v[56:59], 0
	v_cvt_f32_u32_e32 v125, v125
	v_mul_f32_e64 v120, -v124, v120
	v_add_u32_e32 v124, 0x47, v178
	v_cmp_gt_i32_e32 vcc, s22, v124
	v_mfma_f32_16x16x32_bf16 v[104:107], v[104:107], v[52:55], v[108:111]
	s_and_b64 s[0:1], s[2:3], vcc
	v_mul_f32_e32 v120, 0x3fb8aa3b, v120
	v_exp_f32_e32 v120, v120
	s_waitcnt lgkmcnt(0)
	v_mfma_f32_16x16x32_bf16 v[52:55], v[96:99], v[52:55], v[56:59]
	v_mul_f32_e64 v125, -v126, v125
	v_mul_f32_e32 v125, 0x3fb8aa3b, v125
	v_exp_f32_e32 v125, v125
	v_add_u32_e32 v56, 0xffffffa0, v179
	v_sub_u32_e32 v58, 0x60, v179
	v_cmp_gt_i32_e32 vcc, 0, v56
	v_add_u32_e32 v57, 0xffffff9f, v179
	v_max_i32_e32 v58, v56, v58
	v_cndmask_b32_e32 v59, v173, v176, vcc
	v_cmp_lt_i32_e32 vcc, 0, v56
	v_sub_u32_e32 v56, 0x61, v179
	v_cvt_f32_u32_e32 v58, v58
	v_cndmask_b32_e32 v56, v56, v57, vcc
	v_cvt_f32_u32_e32 v56, v56
	v_cndmask_b32_e32 v57, v176, v173, vcc
	v_mul_f32_e64 v58, -v59, v58
	v_cndmask_b32_e64 v120, v120, 0, s[0:1]
	v_mul_f32_e64 v56, -v57, v56
	v_mul_f32_e32 v56, 0x3fb8aa3b, v56
	v_exp_f32_e32 v56, v56
	v_add_u32_e32 v57, 0x61, v178
	v_mul_f32_e32 v58, 0x3fb8aa3b, v58
	v_cmp_gt_i32_e64 s[0:1], s22, v57
	v_exp_f32_e32 v58, v58
	s_and_b64 s[0:1], s[2:3], s[0:1]
	v_cndmask_b32_e64 v56, v56, 0, s[0:1]
	v_cmp_gt_i32_e32 vcc, 2, v177
	v_mul_f32_e32 v52, v56, v52
	v_add_u32_e32 v56, 0xffffff9e, v179
	v_cndmask_b32_e64 v124, v125, 0, s[4:5]
	s_and_b64 s[4:5], s[2:3], vcc
	v_sub_u32_e32 v59, 0x62, v179
	v_cmp_gt_i32_e32 vcc, 0, v56
	v_cndmask_b32_e64 v57, v58, 0, s[4:5]
	v_add_u32_e32 v58, 0xffffff9d, v179
	v_max_i32_e32 v59, v56, v59
	v_cndmask_b32_e32 v96, v173, v176, vcc
	v_cmp_lt_i32_e32 vcc, 0, v56
	v_sub_u32_e32 v56, 0x63, v179
	v_cvt_f32_u32_e32 v59, v59
	v_cndmask_b32_e32 v56, v56, v58, vcc
	v_cvt_f32_u32_e32 v56, v56
	v_cndmask_b32_e32 v58, v176, v173, vcc
	v_mul_f32_e64 v59, -v96, v59
	v_mul_f32_e32 v59, 0x3fb8aa3b, v59
	v_mul_f32_e64 v56, -v58, v56
	v_mul_f32_e32 v56, 0x3fb8aa3b, v56
	v_exp_f32_e32 v56, v56
	v_add_u32_e32 v58, 0x63, v178
	v_cmp_gt_i32_e32 vcc, s22, v58
	v_exp_f32_e32 v59, v59
	s_and_b64 s[0:1], s[2:3], vcc
	v_cndmask_b32_e64 v56, v56, 0, s[0:1]
	v_mul_f32_e32 v53, v56, v53
	v_add_u32_e32 v56, 0xffffff9c, v179
	v_sub_u32_e32 v96, 0x64, v179
	v_cmp_gt_i32_e32 vcc, 0, v56
	v_cndmask_b32_e64 v58, v59, 0, s[4:5]
	v_add_u32_e32 v59, 0xffffff9b, v179
	v_max_i32_e32 v96, v56, v96
	v_cndmask_b32_e32 v97, v173, v176, vcc
	v_cmp_lt_i32_e32 vcc, 0, v56
	v_sub_u32_e32 v56, 0x65, v179
	v_cvt_f32_u32_e32 v96, v96
	v_cndmask_b32_e32 v56, v56, v59, vcc
	v_cvt_f32_u32_e32 v56, v56
	v_cndmask_b32_e32 v59, v176, v173, vcc
	v_mul_f32_e64 v96, -v97, v96
	v_mul_f32_e32 v96, 0x3fb8aa3b, v96
	v_mul_f32_e64 v56, -v59, v56
	v_mul_f32_e32 v56, 0x3fb8aa3b, v56
	v_exp_f32_e32 v56, v56
	v_add_u32_e32 v59, 0x65, v178
	v_cmp_gt_i32_e32 vcc, s22, v59
	v_exp_f32_e32 v96, v96
	s_and_b64 s[0:1], s[2:3], vcc
	v_cndmask_b32_e64 v56, v56, 0, s[0:1]
	v_mul_f32_e32 v54, v56, v54
	v_add_u32_e32 v56, 0xffffff9a, v179
	v_sub_u32_e32 v97, 0x66, v179
	v_cmp_gt_i32_e32 vcc, 0, v56
	v_cndmask_b32_e64 v59, v96, 0, s[4:5]
	v_add_u32_e32 v96, 0xffffff99, v179
	v_max_i32_e32 v97, v56, v97
	v_cndmask_b32_e32 v98, v173, v176, vcc
	v_cmp_lt_i32_e32 vcc, 0, v56
	v_sub_u32_e32 v56, 0x67, v179
	v_cvt_f32_u32_e32 v97, v97
	v_cndmask_b32_e32 v56, v56, v96, vcc
	v_cvt_f32_u32_e32 v56, v56
	v_cndmask_b32_e32 v96, v176, v173, vcc
	v_mul_f32_e64 v97, -v98, v97
	v_mul_f32_e32 v97, 0x3fb8aa3b, v97
	v_mul_f32_e64 v56, -v96, v56
	v_mul_f32_e32 v56, 0x3fb8aa3b, v56
	v_exp_f32_e32 v97, v97
	v_exp_f32_e32 v56, v56
	v_add_u32_e32 v96, 0x67, v178
	v_cmp_gt_i32_e32 vcc, s22, v96
	s_and_b64 s[0:1], s[2:3], vcc
	v_cndmask_b32_e64 v96, v97, 0, s[4:5]
	v_cndmask_b32_e64 v56, v56, 0, s[0:1]
	v_mul_f32_e32 v95, v168, v95
	v_mul_f32_e32 v147, v169, v147
	v_mul_f32_e32 v136, v136, v139
	v_mul_f32_e32 v115, v132, v115
	v_mul_f32_e32 v124, v124, v127
	v_mul_f32_e32 v119, v120, v119
	v_mul_f32_e32 v57, v57, v104
	v_mul_f32_e32 v58, v58, v105
	v_mul_f32_e32 v59, v59, v106
	v_mul_f32_e32 v96, v96, v107
	v_mul_f32_e32 v55, v56, v55
	v_mul_u32_u24_e32 v56, 0x120, v175
	v_readlane_b32 s0, v254, 59
	v_cvt_pk_bf16_f32 v92, v92, v144
	v_cvt_pk_bf16_f32 v93, v93, v145
	v_cvt_pk_bf16_f32 v94, v94, v146
	v_cvt_pk_bf16_f32 v95, v95, v147
	v_cvt_pk_bf16_f32 v112, v133, v112
	v_cvt_pk_bf16_f32 v113, v134, v113
	v_cvt_pk_bf16_f32 v114, v135, v114
	v_cvt_pk_bf16_f32 v115, v136, v115
	v_cvt_pk_bf16_f32 v116, v121, v116
	v_cvt_pk_bf16_f32 v117, v122, v117
	v_cvt_pk_bf16_f32 v118, v123, v118
	v_cvt_pk_bf16_f32 v119, v124, v119
	v_cvt_pk_bf16_f32 v52, v57, v52
	v_cvt_pk_bf16_f32 v53, v58, v53
	v_cvt_pk_bf16_f32 v54, v59, v54
	v_cvt_pk_bf16_f32 v55, v96, v55
	v_add3_u32 v155, s0, v56, v155
	ds_read_b128 v[56:59], v155
	ds_read_b128 v[96:99], v155 offset:64
	ds_read_b128 v[100:103], v155 offset:4608
	ds_read_b128 v[104:107], v155 offset:4672
	ds_read_b128 v[108:111], v155 offset:9216
	ds_read_b128 v[120:123], v155 offset:9280
	ds_read_b128 v[124:127], v155 offset:13824
	ds_read_b128 v[128:131], v155 offset:13888
	ds_read_b128 v[132:135], v155 offset:18432
	ds_read_b128 v[136:139], v155 offset:18496
	ds_read_b128 v[140:143], v155 offset:23040
	ds_read_b128 v[144:147], v155 offset:23104
	ds_read_b128 v[176:179], v155 offset:27648
	ds_read_b128 v[180:183], v155 offset:27712
	ds_read_b128 v[184:187], v155 offset:32256
	ds_read_b128 v[188:191], v155 offset:32320
	s_waitcnt lgkmcnt(14)
	v_mfma_f32_16x16x32_bf16 v[56:59], v[56:59], v[92:95], v[60:63]
	s_waitcnt lgkmcnt(13)
	v_mfma_f32_16x16x32_bf16 v[60:63], v[100:103], v[92:95], v[64:67]
	s_waitcnt lgkmcnt(11)
	v_mfma_f32_16x16x32_bf16 v[64:67], v[108:111], v[92:95], v[68:71]
	s_waitcnt lgkmcnt(9)
	v_mfma_f32_16x16x32_bf16 v[68:71], v[124:127], v[92:95], v[72:75]
	s_waitcnt lgkmcnt(7)
	v_mfma_f32_16x16x32_bf16 v[72:75], v[132:135], v[92:95], v[76:79]
	s_waitcnt lgkmcnt(5)
	v_mfma_f32_16x16x32_bf16 v[76:79], v[140:143], v[92:95], v[80:83]
	s_waitcnt lgkmcnt(3)
	v_mfma_f32_16x16x32_bf16 v[80:83], v[176:179], v[92:95], v[84:87]
	s_waitcnt lgkmcnt(1)
	v_mfma_f32_16x16x32_bf16 v[84:87], v[184:187], v[92:95], v[88:91]
	v_mfma_f32_16x16x32_bf16 v[56:59], v[96:99], v[112:115], v[56:59]
	v_mfma_f32_16x16x32_bf16 v[60:63], v[104:107], v[112:115], v[60:63]
	v_mfma_f32_16x16x32_bf16 v[64:67], v[120:123], v[112:115], v[64:67]
	v_mfma_f32_16x16x32_bf16 v[68:71], v[128:131], v[112:115], v[68:71]
	v_mfma_f32_16x16x32_bf16 v[72:75], v[136:139], v[112:115], v[72:75]
	v_mfma_f32_16x16x32_bf16 v[76:79], v[144:147], v[112:115], v[76:79]
	v_mfma_f32_16x16x32_bf16 v[80:83], v[180:183], v[112:115], v[80:83]
	s_waitcnt lgkmcnt(0)
	v_mfma_f32_16x16x32_bf16 v[84:87], v[188:191], v[112:115], v[84:87]
	ds_read_b128 v[88:91], v155 offset:128
	ds_read_b128 v[92:95], v155 offset:192
	ds_read_b128 v[96:99], v155 offset:4736
	ds_read_b128 v[100:103], v155 offset:4800
	ds_read_b128 v[104:107], v155 offset:9344
	ds_read_b128 v[108:111], v155 offset:9408
	ds_read_b128 v[112:115], v155 offset:13952
	ds_read_b128 v[120:123], v155 offset:14016
	ds_read_b128 v[124:127], v155 offset:18560
	ds_read_b128 v[128:131], v155 offset:18624
	ds_read_b128 v[132:135], v155 offset:23168
	ds_read_b128 v[136:139], v155 offset:23232
	ds_read_b128 v[140:143], v155 offset:27776
	ds_read_b128 v[144:147], v155 offset:27840
	ds_read_b128 v[176:179], v155 offset:32384
	ds_read_b128 v[180:183], v155 offset:32448
	s_waitcnt lgkmcnt(14)
	v_mfma_f32_16x16x32_bf16 v[56:59], v[88:91], v[116:119], v[56:59]
	s_waitcnt lgkmcnt(13)
	v_mfma_f32_16x16x32_bf16 v[60:63], v[96:99], v[116:119], v[60:63]
	s_waitcnt lgkmcnt(11)
	v_mfma_f32_16x16x32_bf16 v[64:67], v[104:107], v[116:119], v[64:67]
	s_waitcnt lgkmcnt(9)
	v_mfma_f32_16x16x32_bf16 v[68:71], v[112:115], v[116:119], v[68:71]
	s_waitcnt lgkmcnt(7)
	v_mfma_f32_16x16x32_bf16 v[88:91], v[124:127], v[116:119], v[72:75]
	s_waitcnt lgkmcnt(5)
	v_mfma_f32_16x16x32_bf16 v[96:99], v[132:135], v[116:119], v[76:79]
	s_waitcnt lgkmcnt(3)
	v_mfma_f32_16x16x32_bf16 v[104:107], v[140:143], v[116:119], v[80:83]
	s_waitcnt lgkmcnt(1)
	v_mfma_f32_16x16x32_bf16 v[84:87], v[176:179], v[116:119], v[84:87]
	v_mfma_f32_16x16x32_bf16 v[80:83], v[92:95], v[52:55], v[56:59]
	v_mfma_f32_16x16x32_bf16 v[76:79], v[100:103], v[52:55], v[60:63]
	v_mfma_f32_16x16x32_bf16 v[72:75], v[108:111], v[52:55], v[64:67]
	v_mfma_f32_16x16x32_bf16 v[68:71], v[120:123], v[52:55], v[68:71]
	v_mfma_f32_16x16x32_bf16 v[64:67], v[128:131], v[52:55], v[88:91]
	v_mfma_f32_16x16x32_bf16 v[60:63], v[136:139], v[52:55], v[96:99]
	v_mfma_f32_16x16x32_bf16 v[56:59], v[144:147], v[52:55], v[104:107]
	s_waitcnt lgkmcnt(0)
	v_mfma_f32_16x16x32_bf16 v[52:55], v[180:183], v[52:55], v[84:87]
	s_nop 2
	v_mov_b32_e32 v84, v80
	v_mov_b32_e32 v85, v76
	v_mov_b32_e32 v86, v81
	v_mov_b32_e32 v87, v77
	v_pk_add_f32 v[84:85], v[84:85], v[86:87]
	v_mov_b32_e32 v86, v82
	v_mov_b32_e32 v87, v78
	v_mov_b32_e32 v88, v83
	v_mov_b32_e32 v89, v79
	v_pk_add_f32 v[86:87], v[86:87], v[88:89]
	v_mov_b32_e32 v88, v72
	v_pk_add_f32 v[84:85], v[84:85], v[86:87]
	v_mov_b32_e32 v86, v73
	v_mov_b32_e32 v87, v74
	v_mov_b32_e32 v89, v75
	v_pk_add_f32 v[86:87], v[86:87], v[88:89]
	v_add_f32_e32 v84, 0, v84
	v_pk_add_f32 v[86:87], v[86:87], v[86:87] op_sel:[0,1] op_sel_hi:[1,0]
	v_add_f32_e32 v84, v84, v85
	v_add_f32_e32 v88, v68, v69
	v_add_f32_e32 v90, v70, v71
	v_mov_b32_e32 v85, v64
	v_mov_b32_e32 v87, v65
	v_mov_b32_e32 v89, v66
	v_mov_b32_e32 v91, v67
	v_pk_add_f32 v[84:85], v[84:85], v[86:87]
	v_pk_add_f32 v[86:87], v[88:89], v[90:91]
	v_mov_b32_e32 v88, v60
	v_pk_add_f32 v[84:85], v[84:85], v[86:87]
	v_mov_b32_e32 v86, v61
	v_mov_b32_e32 v87, v62
	v_mov_b32_e32 v89, v63
	v_pk_add_f32 v[86:87], v[86:87], v[88:89]
	v_pk_add_f32 v[84:85], v[84:85], v[84:85] op_sel:[0,1] op_sel_hi:[1,0]
	v_pk_add_f32 v[86:87], v[86:87], v[86:87] op_sel:[0,1] op_sel_hi:[1,0]
	v_add_f32_e32 v88, v56, v57
	v_add_f32_e32 v90, v58, v59
	v_mov_b32_e32 v85, v52
	v_mov_b32_e32 v87, v53
	v_mov_b32_e32 v89, v54
	v_mov_b32_e32 v91, v55
	v_pk_add_f32 v[84:85], v[84:85], v[86:87]
	v_pk_add_f32 v[86:87], v[88:89], v[90:91]
	v_and_b32_e32 v2, 16, v2
	v_pk_add_f32 v[84:85], v[84:85], v[86:87]
	v_and_b32_e32 v86, 64, v217
	v_add_f32_e32 v84, v84, v85
	v_xor_b32_e32 v85, 16, v217
	v_add_u32_e32 v86, 64, v86
	v_cmp_lt_i32_e32 vcc, v85, v86
	v_lshlrev_b32_e32 v2, 1, v2
	s_nop 0
	v_cndmask_b32_e32 v85, v217, v85, vcc
	v_lshlrev_b32_e32 v94, 2, v85
	v_mov_b32_e32 v85, v84
	s_nop 1
	v_permlane16_swap_b32_e32 v85, v84
	s_nop 1
	s_waitcnt lgkmcnt(0)
	v_add_f32_e32 v84, v84, v85
	v_xor_b32_e32 v85, 32, v217
	v_cmp_lt_i32_e32 vcc, v85, v86
	s_nop 1
	v_cndmask_b32_e32 v85, v217, v85, vcc
	v_lshlrev_b32_e32 v95, 2, v85
	v_mov_b32_e32 v85, v84
	s_nop 1
	v_permlane32_swap_b32_e32 v85, v84
	s_nop 1
	s_waitcnt lgkmcnt(0)
	v_add_f32_e32 v96, v84, v85
	v_fmamk_f32 v81, v96, 0xbc000000, v81
	v_fmamk_f32 v77, v96, 0xbc000000, v77
	v_fmamk_f32 v83, v96, 0xbc000000, v83
	v_fmac_f32_e32 v80, 0xbc000000, v96
	v_fmamk_f32 v79, v96, 0xbc000000, v79
	v_fmac_f32_e32 v76, 0xbc000000, v96
	v_mov_b32_e32 v86, v81
	v_mov_b32_e32 v87, v77
	v_fmamk_f32 v82, v96, 0xbc000000, v82
	v_fmamk_f32 v78, v96, 0xbc000000, v78
	v_mov_b32_e32 v84, v80
	v_mov_b32_e32 v85, v76
	v_pk_mul_f32 v[86:87], v[86:87], v[86:87]
	v_mov_b32_e32 v88, v83
	v_mov_b32_e32 v89, v79
	v_pk_fma_f32 v[84:85], v[84:85], v[84:85], v[86:87]
	v_mov_b32_e32 v86, v82
	v_mov_b32_e32 v87, v78
	v_pk_mul_f32 v[88:89], v[88:89], v[88:89]
	v_fmamk_f32 v73, v96, 0xbc000000, v73
	v_pk_fma_f32 v[86:87], v[86:87], v[86:87], v[88:89]
	v_fmamk_f32 v72, v96, 0xbc000000, v72
	v_pk_add_f32 v[84:85], v[84:85], v[86:87]
	v_fmamk_f32 v75, v96, 0xbc000000, v75
	v_fmac_f32_e32 v74, 0xbc000000, v96
	v_pk_add_f32 v[84:85], v[84:85], v[84:85] op_sel_hi:[0,1]
	v_pk_mul_f32 v[86:87], v[74:75], v[74:75]
	v_pk_mul_f32 v[88:89], v[72:73], v[72:73]
	v_fmamk_f32 v68, v96, 0xbc000000, v68
	v_pk_mov_b32 v[90:91], v[88:89], v[86:87] op_sel:[1,0]
	v_mov_b32_e32 v89, v87
	v_fmamk_f32 v69, v96, 0xbc000000, v69
	v_fmac_f32_e32 v70, 0xbc000000, v96
	v_mul_f32_e32 v84, v68, v68
	v_pk_add_f32 v[86:87], v[90:91], v[88:89]
	v_fmamk_f32 v71, v96, 0xbc000000, v71
	v_pk_fma_f32 v[88:89], v[68:69], v[68:69], v[84:85] op_sel_hi:[1,1,0]
	v_mul_f32_e32 v84, v70, v70
	v_pk_add_f32 v[86:87], v[86:87], v[86:87] op_sel_hi:[0,1]
	v_pk_fma_f32 v[90:91], v[70:71], v[70:71], v[84:85] op_sel_hi:[1,1,0]
	v_fmamk_f32 v67, v96, 0xbc000000, v67
	v_fmamk_f32 v66, v96, 0xbc000000, v66
	v_fmamk_f32 v65, v96, 0xbc000000, v65
	v_fmac_f32_e32 v64, 0xbc000000, v96
	v_mul_f32_e32 v88, v64, v64
	v_mul_f32_e32 v90, v65, v65
	v_mul_f32_e32 v86, v66, v66
	v_mul_f32_e32 v84, v67, v67
	v_pk_add_f32 v[88:89], v[88:89], v[90:91]
	v_pk_add_f32 v[84:85], v[86:87], v[84:85]
	v_fmamk_f32 v61, v96, 0xbc000000, v61
	v_fmamk_f32 v60, v96, 0xbc000000, v60
	v_fmamk_f32 v63, v96, 0xbc000000, v63
	v_fmac_f32_e32 v62, 0xbc000000, v96
	v_pk_add_f32 v[84:85], v[88:89], v[84:85]
	v_pk_mul_f32 v[86:87], v[62:63], v[62:63]
	v_pk_mul_f32 v[88:89], v[60:61], v[60:61]
	v_fmac_f32_e32 v58, 0xbc000000, v96
	v_pk_mov_b32 v[90:91], v[88:89], v[86:87] op_sel:[1,0]
	v_mov_b32_e32 v89, v87
	v_pk_add_f32 v[86:87], v[90:91], v[88:89]
	v_fmamk_f32 v88, v96, 0xbc000000, v56
	v_fmamk_f32 v89, v96, 0xbc000000, v57
	v_mul_f32_e32 v56, v88, v88
	v_pk_fma_f32 v[56:57], v[88:89], v[88:89], v[56:57] op_sel_hi:[1,1,0]
	v_fmamk_f32 v59, v96, 0xbc000000, v59
	v_mul_f32_e32 v56, v58, v58
	v_pk_add_f32 v[84:85], v[84:85], v[84:85] op_sel_hi:[0,1]
	v_pk_add_f32 v[86:87], v[86:87], v[86:87] op_sel_hi:[0,1]
	v_pk_fma_f32 v[90:91], v[58:59], v[58:59], v[56:57] op_sel_hi:[1,1,0]
	v_fmamk_f32 v93, v96, 0xbc000000, v55
	v_fmamk_f32 v92, v96, 0xbc000000, v54
	v_fmamk_f32 v53, v96, 0xbc000000, v53
	v_fmac_f32_e32 v52, 0xbc000000, v96
	v_mul_f32_e32 v56, v52, v52
	v_mul_f32_e32 v90, v53, v53
	v_mul_f32_e32 v86, v92, v92
	v_mul_f32_e32 v84, v93, v93
	v_pk_add_f32 v[54:55], v[56:57], v[90:91]
	v_pk_add_f32 v[56:57], v[86:87], v[84:85]
	v_mov_b64_e32 v[96:97], s[96:97]
	v_pk_add_f32 v[54:55], v[54:55], v[56:57]
	s_waitcnt vmcnt(7)
	v_lshlrev_b32_e32 v56, 16, v163
	v_add_f32_e32 v54, v54, v55
	v_mov_b32_e32 v55, v54
	s_nop 1
	v_permlane16_swap_b32_e32 v55, v54
	s_nop 1
	v_and_b32_e32 v57, 0xffff0000, v163
	s_waitcnt vmcnt(6)
	v_lshlrev_b32_e32 v90, 16, v160
	v_and_b32_e32 v91, 0xffff0000, v160
	v_lshlrev_b32_e32 v94, 16, v161
	s_waitcnt lgkmcnt(0)
	v_add_f32_e32 v54, v54, v55
	v_mov_b32_e32 v55, v54
	s_nop 1
	v_permlane32_swap_b32_e32 v55, v54
	s_nop 1
	v_and_b32_e32 v95, 0xffff0000, v161
	v_mad_i64_i32 v[96:97], s[0:1], v154, s48, v[96:97]
	v_and_b32_e32 v86, -8, v172
	s_waitcnt lgkmcnt(0)
	v_add_f32_e32 v54, v54, v55
	v_fmamk_f32 v54, v54, 0x3c000000, v219
	v_mul_f32_e32 v55, 0x4b800000, v54
	v_cmp_gt_f32_e32 vcc, s35, v54
	v_lshl_add_u64 v[96:97], v[96:97], 0, s[18:19]
	v_ashrrev_i32_e32 v87, 31, v86
	v_cndmask_b32_e32 v54, v54, v55, vcc
	v_rsq_f32_e32 v54, v54
	s_nop 0
	v_mul_f32_e32 v55, 0x45800000, v54
	v_cndmask_b32_e32 v84, v54, v55, vcc
	v_lshlrev_b32_e32 v54, 16, v162
	v_and_b32_e32 v55, 0xffff0000, v162
	v_pk_mul_f32 v[80:81], v[80:81], v[84:85] op_sel_hi:[1,0]
	v_pk_mul_f32 v[82:83], v[82:83], v[84:85] op_sel_hi:[1,0]
	v_pk_mul_f32 v[76:77], v[76:77], v[84:85] op_sel_hi:[1,0]
	v_pk_mul_f32 v[78:79], v[78:79], v[84:85] op_sel_hi:[1,0]
	v_pk_mul_f32 v[56:57], v[82:83], v[56:57]
	v_pk_mul_f32 v[54:55], v[80:81], v[54:55]
	v_pk_mul_f32 v[78:79], v[78:79], v[94:95]
	v_pk_mul_f32 v[76:77], v[76:77], v[90:91]
	v_cvt_pk_bf16_f32 v54, v54, v55
	v_cvt_pk_bf16_f32 v55, v56, v57
	v_cvt_pk_bf16_f32 v56, v76, v77
	v_cvt_pk_bf16_f32 v57, v78, v79
	v_lshl_add_u64 v[76:77], v[96:97], 0, v[2:3]
	v_permlane16_swap_b32_e32 v54, v56
	v_permlane16_swap_b32_e32 v55, v57
	v_lshl_add_u64 v[76:77], v[86:87], 1, v[76:77]
	global_store_dwordx4 v[76:77], v[54:57], off
	s_waitcnt vmcnt(5)
	v_lshlrev_b32_e32 v78, 16, v156
	v_and_b32_e32 v79, 0xffff0000, v156
	v_lshlrev_b32_e32 v54, 16, v158
	v_and_b32_e32 v55, 0xffff0000, v158
	v_lshlrev_b32_e32 v56, 16, v159
	v_and_b32_e32 v57, 0xffff0000, v159
	v_lshlrev_b32_e32 v80, 16, v157
	v_and_b32_e32 v81, 0xffff0000, v157
	v_pk_mul_f32 v[72:73], v[72:73], v[84:85] op_sel_hi:[1,0]
	v_pk_mul_f32 v[74:75], v[74:75], v[84:85] op_sel_hi:[1,0]
	v_pk_mul_f32 v[68:69], v[68:69], v[84:85] op_sel_hi:[1,0]
	v_pk_mul_f32 v[70:71], v[70:71], v[84:85] op_sel_hi:[1,0]
	v_pk_mul_f32 v[56:57], v[74:75], v[56:57]
	v_pk_mul_f32 v[54:55], v[72:73], v[54:55]
	v_pk_mul_f32 v[70:71], v[70:71], v[80:81]
	v_pk_mul_f32 v[68:69], v[68:69], v[78:79]
	v_cvt_pk_bf16_f32 v54, v54, v55
	v_cvt_pk_bf16_f32 v55, v56, v57
	v_cvt_pk_bf16_f32 v56, v68, v69
	v_cvt_pk_bf16_f32 v57, v70, v71
	s_nop 0
	v_permlane16_swap_b32_e32 v54, v56
	v_permlane16_swap_b32_e32 v55, v57
	global_store_dwordx4 v[76:77], v[54:57], off offset:64
	s_waitcnt vmcnt(4)
	v_lshlrev_b32_e32 v68, 16, v150
	v_and_b32_e32 v69, 0xffff0000, v150
	v_lshlrev_b32_e32 v54, 16, v152
	v_and_b32_e32 v55, 0xffff0000, v152
	v_lshlrev_b32_e32 v56, 16, v153
	v_and_b32_e32 v57, 0xffff0000, v153
	v_lshlrev_b32_e32 v70, 16, v151
	v_and_b32_e32 v71, 0xffff0000, v151
	v_pk_mul_f32 v[64:65], v[64:65], v[84:85] op_sel_hi:[1,0]
	v_pk_mul_f32 v[66:67], v[66:67], v[84:85] op_sel_hi:[1,0]
	v_pk_mul_f32 v[60:61], v[60:61], v[84:85] op_sel_hi:[1,0]
	v_pk_mul_f32 v[62:63], v[62:63], v[84:85] op_sel_hi:[1,0]
	v_pk_mul_f32 v[56:57], v[66:67], v[56:57]
	v_pk_mul_f32 v[54:55], v[64:65], v[54:55]
	v_pk_mul_f32 v[62:63], v[62:63], v[70:71]
	v_pk_mul_f32 v[60:61], v[60:61], v[68:69]
	v_cvt_pk_bf16_f32 v54, v54, v55
	v_cvt_pk_bf16_f32 v55, v56, v57
	v_cvt_pk_bf16_f32 v56, v60, v61
	v_cvt_pk_bf16_f32 v57, v62, v63
	s_nop 0
	v_permlane16_swap_b32_e32 v54, v56
	v_permlane16_swap_b32_e32 v55, v57
	global_store_dwordx4 v[76:77], v[54:57], off offset:128
	v_pk_mul_f32 v[58:59], v[58:59], v[84:85] op_sel_hi:[1,0]
	s_waitcnt vmcnt(3)
	v_lshlrev_b32_e32 v60, 16, v0
	v_lshlrev_b32_e32 v56, 16, v149
	v_and_b32_e32 v57, 0xffff0000, v149
	v_lshlrev_b32_e32 v54, 16, v148
	v_and_b32_e32 v55, 0xffff0000, v148
	v_and_b32_e32 v61, 0xffff0000, v0
	v_lshlrev_b32_e32 v0, 16, v1
	v_and_b32_e32 v1, 0xffff0000, v1
	v_pk_mul_f32 v[62:63], v[88:89], v[84:85] op_sel_hi:[1,0]
	v_pk_mul_f32 v[56:57], v[58:59], v[56:57]
	v_pk_mul_f32 v[52:53], v[52:53], v[84:85] op_sel_hi:[1,0]
	v_pk_mul_f32 v[58:59], v[92:93], v[84:85] op_sel_hi:[1,0]
	v_pk_mul_f32 v[54:55], v[62:63], v[54:55]
	v_pk_mul_f32 v[0:1], v[58:59], v[0:1]
	v_pk_mul_f32 v[58:59], v[52:53], v[60:61]
	v_cvt_pk_bf16_f32 v52, v54, v55
	v_cvt_pk_bf16_f32 v53, v56, v57
	v_cvt_pk_bf16_f32 v54, v58, v59
	v_cvt_pk_bf16_f32 v55, v0, v1
	s_nop 0
	v_permlane16_swap_b32_e32 v52, v54
	v_permlane16_swap_b32_e32 v53, v55
	global_store_dwordx4 v[76:77], v[52:55], off offset:192
	v_readlane_b32 s0, v254, 18
	s_waitcnt vmcnt(4)
	s_branch .Lret_join
